# remaining 34 flat loads (FFN gated-conv loop, layer-0 row loads, attention Q fragments) also converted to global loads
# baseline (speedup 1.0000x reference)
; __device__ __forceinline__ float bf_lo(unsigned w) { return __uint_as_float(w << 16); }
; __global__ void __launch_bounds__(512, 2) mk_fwd(Args a) {
;     ...
;                 for (int lb = l0; lb < l1; lb += 4) {
;                     u32x4 x[6][2];
; #pragma unroll
;                     for (int i = 0; i < 6; ++i) { const int lg = lb - 1 + i; const bool ok = lg >= 0 && lg < LSEQ; const bf16_t* p = U + (size_t)(ok ? phys_of(lg) : 0) * NUP + c;
;                         x[i][0] = *(const u32x4*)p; x[i][1] = *(const u32x4*)(p + DFF);
;                         if (!ok) { x[i][0] = (u32x4){0u, 0u, 0u, 0u}; x[i][1] = (u32x4){0u, 0u, 0u, 0u}; } }
; #pragma unroll
;                     for (int i = 0; i < 4; ++i) { const int lg = lb + i; if (lg < l1) {
;                         f32x4 av[2], bv[2];
; #pragma unroll
;                         for (int hh = 0; hh < 2; ++hh) {
;                             f32x4 x0, x1, x2, y0, y1, y2;
;                             const unsigned a0 = hh ? x[i][0].z : x[i][0].x, a1 = hh ? x[i][0].w : x[i][0].y, b0 = hh ? x[i + 1][0].z : x[i + 1][0].x, b1 = hh ? x[i + 1][0].w : x[i + 1][0].y, c0 = hh ? x[i + 2][0].z : x[i + 2][0].x, c1 = hh ? x[i + 2][0].w : x[i + 2][0].y;
;                             x0 = (f32x4){bf_lo(a0), bf_hi(a0), bf_lo(a1), bf_hi(a1)}; x1 = (f32x4){bf_lo(b0), bf_hi(b0), bf_lo(b1), bf_hi(b1)}; x2 = (f32x4){bf_lo(c0), bf_hi(c0), bf_lo(c1), bf_hi(c1)};
;                             const unsigned d0 = hh ? x[i][1].z : x[i][1].x, d1 = hh ? x[i][1].w : x[i][1].y, e0 = hh ? x[i + 1][1].z : x[i + 1][1].x, e1 = hh ? x[i + 1][1].w : x[i + 1][1].y, f0 = hh ? x[i + 2][1].z : x[i + 2][1].x, f1 = hh ? x[i + 2][1].w : x[i + 2][1].y;
;                             y0 = (f32x4){bf_lo(d0), bf_hi(d0), bf_lo(d1), bf_hi(d1)}; y1 = (f32x4){bf_lo(e0), bf_hi(e0), bf_lo(e1), bf_hi(e1)}; y2 = (f32x4){bf_lo(f0), bf_hi(f0), bf_lo(f1), bf_hi(f1)};
;                             av[hh] = wt[0][0][hh] * x0 + wt[1][0][hh] * x1 + wt[2][0][hh] * x2;
;                             bv[hh] = wt[0][1][hh] * y0 + wt[1][1][hh] * y1 + wt[2][1][hh] * y2; }
;                         u32x4 o;
;                         o.x = cvt_pk_bf16(av[0][0] * sigm(av[0][0]) * bv[0][0], av[0][1] * sigm(av[0][1]) * bv[0][1]); o.y = cvt_pk_bf16(av[0][2] * sigm(av[0][2]) * bv[0][2], av[0][3] * sigm(av[0][3]) * bv[0][3]);
.LBB0_88:
	s_waitcnt vmcnt(0) lgkmcnt(0)
	v_lshl_add_u64 v[48:49], s[0:1], 1, v[88:89]
	v_add_co_u32_e32 v52, vcc, 0x2000, v48
	s_cmpk_lt_u32 s8, 0x2010
	s_nop 0
	v_addc_co_u32_e32 v53, vcc, 0, v49, vcc
	global_load_dwordx4 v[48:51], v[48:49], off
	s_nop 0
	global_load_dwordx4 v[52:55], v[52:53], off offset:3072
	s_cselect_b64 s[0:1], -1, 0
	s_cmpk_gt_u32 s8, 0x200f
	s_cbranch_scc1 .LBB0_90
	s_cmp_gt_u32 s8, 15
	s_cselect_b32 s13, -16, 0x2000
	s_add_i32 s13, s8, s13
	s_mul_i32 s36, s13, 0x2c00
	s_ashr_i32 s37, s36, 31
.LBB0_90:
	v_lshl_add_u64 v[56:57], s[36:37], 1, v[88:89]
	v_add_co_u32_e32 v58, vcc, 0x2000, v56
	s_mov_b64 s[36:37], 0
	s_nop 0
	v_addc_co_u32_e32 v59, vcc, 0, v57, vcc
	global_load_dwordx4 v[64:67], v[56:57], off
	global_load_dwordx4 v[68:71], v[58:59], off offset:3072
	v_cndmask_b32_e64 v56, 0, 1, s[0:1]
	v_cmp_ne_u32_e64 s[40:41], 1, v56
	s_andn2_b64 vcc, exec, s[0:1]
	s_mov_b64 s[48:49], 0
	s_cbranch_vccnz .LBB0_92
	s_cmp_gt_u32 s8, 15
	s_cselect_b32 s13, -16, 0x2000
	s_add_i32 s13, s8, s13
	s_mulk_i32 s13, 0x2c00
	s_add_i32 s48, s13, 0x2c00
	s_ashr_i32 s49, s48, 31
.LBB0_92:
	v_lshl_add_u64 v[56:57], s[48:49], 1, v[88:89]
	v_add_co_u32_e32 v58, vcc, 0x2000, v56
	s_nop 1
	v_addc_co_u32_e32 v59, vcc, 0, v57, vcc
	global_load_dwordx4 v[72:75], v[56:57], off
	global_load_dwordx4 v[76:79], v[58:59], off offset:3072
	s_and_b64 vcc, exec, s[40:41]
	s_cbranch_vccnz .LBB0_94
	s_cmp_gt_u32 s8, 15
	s_cselect_b32 s13, -16, 0x2000
	s_add_i32 s13, s8, s13
	s_mulk_i32 s13, 0x2c00
	s_add_i32 s36, s13, 0x5800
	s_ashr_i32 s37, s36, 31
.LBB0_94:
	v_lshl_add_u64 v[56:57], s[36:37], 1, v[88:89]
	v_add_co_u32_e32 v58, vcc, 0x2000, v56
	s_mov_b64 s[48:49], 0
	s_nop 0
	v_addc_co_u32_e32 v59, vcc, 0, v57, vcc
	global_load_dwordx4 v[80:83], v[56:57], off
	global_load_dwordx4 v[84:87], v[58:59], off offset:3072
	s_and_b64 vcc, exec, s[40:41]
	s_mov_b64 s[36:37], 0
	s_cbranch_vccnz .LBB0_96
	s_cmp_gt_u32 s8, 15
	s_cselect_b32 s13, -16, 0x2000
	s_add_i32 s13, s8, s13
	s_mulk_i32 s13, 0x2c00
	s_add_i32 s36, s13, 0x8400
	s_ashr_i32 s37, s36, 31
.LBB0_96:
	v_lshl_add_u64 v[56:57], s[36:37], 1, v[88:89]
	v_add_co_u32_e32 v60, vcc, 0x2000, v56
	s_add_u32 s36, s8, 4
	s_nop 0
	v_addc_co_u32_e32 v61, vcc, 0, v57, vcc
	global_load_dwordx4 v[56:59], v[56:57], off
	s_nop 0
	global_load_dwordx4 v[60:63], v[60:61], off offset:3072
	s_addc_u32 s37, s9, 0
	s_cmpk_lt_u32 s36, 0x2010
	s_cselect_b64 vcc, -1, 0
	s_cmpk_gt_u32 s36, 0x200f
	s_cbranch_scc1 .LBB0_98
	s_cmp_gt_u32 s36, 15
	s_cselect_b32 s13, -16, 0x2000
	s_add_i32 s13, s8, s13
	s_mulk_i32 s13, 0x2c00
	s_add_i32 s48, s13, 0xb000
	s_ashr_i32 s49, s48, 31
.LBB0_98:
	s_waitcnt vmcnt(0) lgkmcnt(0)
	v_cndmask_b32_e64 v122, 0, v86, s[0:1]
	v_cndmask_b32_e64 v86, 0, v75, s[0:1]
	v_cndmask_b32_e64 v75, 0, v68, s[0:1]
	v_cndmask_b32_e64 v92, 0, v67, s[0:1]
	v_cndmask_b32_e64 v68, 0, v65, s[0:1]
	v_cndmask_b32_e64 v67, 0, v49, s[38:39]
	v_cndmask_b32_e64 v65, 0, v48, s[38:39]
	v_lshl_add_u64 v[48:49], s[48:49], 1, v[88:89]
	v_cndmask_b32_e64 v115, 0, v71, s[0:1]
	v_cndmask_b32_e64 v113, 0, v70, s[0:1]
	v_cndmask_b32_e64 v97, 0, v55, s[38:39]
	v_cndmask_b32_e64 v96, 0, v54, s[38:39]
	v_cndmask_b32_e64 v71, 0, v53, s[38:39]
	v_cndmask_b32_e64 v70, 0, v52, s[38:39]
	v_cndmask_b32_e64 v94, 0, v51, s[38:39]
	v_cndmask_b32_e64 v95, 0, v50, s[38:39]
	v_add_co_u32_e64 v52, s[38:39], s19, v48
	v_cndmask_b32_e64 v117, 0, v87, s[0:1]
	s_nop 0
	v_addc_co_u32_e64 v53, s[38:39], 0, v49, s[38:39]
	global_load_dwordx4 v[48:51], v[48:49], off
	s_nop 0
	global_load_dwordx4 v[52:55], v[52:53], off offset:3072
	v_cndmask_b32_e64 v87, 0, v74, s[0:1]
	v_cndmask_b32_e64 v74, 0, v69, s[0:1]
	v_cndmask_b32_e64 v69, 0, v64, s[0:1]
	v_lshlrev_b32_e32 v100, 16, v69
	v_and_b32_e32 v101, 0xffff0000, v69
	v_cndmask_b32_e64 v125, 0, v83, s[0:1]
	v_cndmask_b32_e64 v126, 0, v82, s[0:1]
	v_lshlrev_b32_e32 v64, 16, v65
	v_and_b32_e32 v65, 0xffff0000, v65
	v_lshlrev_b32_e32 v104, 16, v75
	v_and_b32_e32 v105, 0xffff0000, v75
	v_pk_mul_f32 v[82:83], v[16:17], v[100:101]
	v_cndmask_b32_e64 v72, 0, v72, s[0:1]
	v_lshlrev_b32_e32 v102, 16, v68
	v_and_b32_e32 v103, 0xffff0000, v68
	v_lshlrev_b32_e32 v68, 16, v70
	v_and_b32_e32 v69, 0xffff0000, v70
	v_pk_fma_f32 v[64:65], v[4:5], v[64:65], v[82:83]
	v_pk_mul_f32 v[82:83], v[24:25], v[104:105]
	v_lshlrev_b32_e32 v110, 16, v92
	v_and_b32_e32 v111, 0xffff0000, v92
	v_cndmask_b32_e64 v123, 0, v85, s[0:1]
	v_cndmask_b32_e64 v124, 0, v84, s[0:1]
	v_cndmask_b32_e64 v85, 0, v79, s[0:1]
	v_cndmask_b32_e64 v84, 0, v78, s[0:1]
	v_cndmask_b32_e64 v93, 0, v66, s[0:1]
	v_lshlrev_b32_e32 v78, 16, v72
	v_and_b32_e32 v79, 0xffff0000, v72
	v_pk_fma_f32 v[68:69], v[8:9], v[68:69], v[82:83]
	v_lshlrev_b32_e32 v82, 16, v94
	v_and_b32_e32 v83, 0xffff0000, v94
	v_lshlrev_b32_e32 v114, 16, v115
	v_and_b32_e32 v115, 0xffff0000, v115
	v_pk_mul_f32 v[118:119], v[22:23], v[110:111]
	v_pk_fma_f32 v[64:65], v[32:33], v[78:79], v[64:65]
	v_lshlrev_b32_e32 v108, 16, v93
	v_and_b32_e32 v109, 0xffff0000, v93
	v_lshlrev_b32_e32 v92, 16, v96
	v_and_b32_e32 v93, 0xffff0000, v96
	v_lshlrev_b32_e32 v96, 16, v97
	v_and_b32_e32 v97, 0xffff0000, v97
	v_pk_fma_f32 v[82:83], v[2:3], v[82:83], v[118:119]
	v_pk_mul_f32 v[118:119], v[30:31], v[114:115]
	v_cndmask_b32_e64 v127, 0, v81, s[0:1]
	v_pk_fma_f32 v[96:97], v[14:15], v[96:97], v[118:119]
	v_mul_f32_e32 v118, 0xbfb8aa3b, v64
	v_exp_f32_e32 v118, v118
	v_mul_f32_e32 v119, 0xbfb8aa3b, v65
	v_exp_f32_e32 v119, v119
	v_cndmask_b32_e64 v128, 0, v80, s[0:1]
	v_add_f32_e32 v118, 1.0, v118
	v_rcp_f32_e32 v118, v118
	v_cndmask_b32_e64 v80, 0, v77, s[0:1]
	v_cndmask_b32_e64 v81, 0, v76, s[0:1]
; __device__ __forceinline__ unsigned cvt_pk_bf16(float lo, float hi) { unsigned r; asm volatile("v_cvt_pk_bf16_f32 %0, %1, %2" : "=v"(r) : "v"(lo), "v"(hi)); return r; }
; __device__ __forceinline__ float bf_lo(unsigned w) { return __uint_as_float(w << 16); }
; __device__ __forceinline__ float bf_hi(unsigned w) { return __uint_as_float(w & 0xffff0000u); }
; __global__ void __launch_bounds__(512, 2) mk_fwd(Args a) {
;     ...
;                     for (int i = 0; i < 4; ++i) { const int lg = lb + i; if (lg < l1) {
;                         f32x4 av[2], bv[2];
; #pragma unroll
;                         for (int hh = 0; hh < 2; ++hh) {
;                             f32x4 x0, x1, x2, y0, y1, y2;
;                             const unsigned a0 = hh ? x[i][0].z : x[i][0].x, a1 = hh ? x[i][0].w : x[i][0].y, b0 = hh ? x[i + 1][0].z : x[i + 1][0].x, b1 = hh ? x[i + 1][0].w : x[i + 1][0].y, c0 = hh ? x[i + 2][0].z : x[i + 2][0].x, c1 = hh ? x[i + 2][0].w : x[i + 2][0].y;
;                             x0 = (f32x4){bf_lo(a0), bf_hi(a0), bf_lo(a1), bf_hi(a1)}; x1 = (f32x4){bf_lo(b0), bf_hi(b0), bf_lo(b1), bf_hi(b1)}; x2 = (f32x4){bf_lo(c0), bf_hi(c0), bf_lo(c1), bf_hi(c1)};
;                             const unsigned d0 = hh ? x[i][1].z : x[i][1].x, d1 = hh ? x[i][1].w : x[i][1].y, e0 = hh ? x[i + 1][1].z : x[i + 1][1].x, e1 = hh ? x[i + 1][1].w : x[i + 1][1].y, f0 = hh ? x[i + 2][1].z : x[i + 2][1].x, f1 = hh ? x[i + 2][1].w : x[i + 2][1].y;
;                             y0 = (f32x4){bf_lo(d0), bf_hi(d0), bf_lo(d1), bf_hi(d1)}; y1 = (f32x4){bf_lo(e0), bf_hi(e0), bf_lo(e1), bf_hi(e1)}; y2 = (f32x4){bf_lo(f0), bf_hi(f0), bf_lo(f1), bf_hi(f1)};
;                             av[hh] = wt[0][0][hh] * x0 + wt[1][0][hh] * x1 + wt[2][0][hh] * x2;
;                             bv[hh] = wt[0][1][hh] * y0 + wt[1][1][hh] * y1 + wt[2][1][hh] * y2; }
;                         u32x4 o;
;                         o.x = cvt_pk_bf16(av[0][0] * sigm(av[0][0]) * bv[0][0], av[0][1] * sigm(av[0][1]) * bv[0][1]); o.y = cvt_pk_bf16(av[0][2] * sigm(av[0][2]) * bv[0][2], av[0][3] * sigm(av[0][3]) * bv[0][3]);
;                         o.z = cvt_pk_bf16(av[1][0] * sigm(av[1][0]) * bv[1][0], av[1][1] * sigm(av[1][1]) * bv[1][1]); o.w = cvt_pk_bf16(av[1][2] * sigm(av[1][2]) * bv[1][2], av[1][3] * sigm(av[1][3]) * bv[1][3]);
;                         *(u32x4*)(GT + (size_t)phys_of(lg) * DFF + c) = o; } }
	v_cndmask_b32_e64 v73, 0, v73, s[0:1]
	v_lshlrev_b32_e32 v66, 16, v67
	v_and_b32_e32 v67, 0xffff0000, v67
	v_lshlrev_b32_e32 v76, 16, v73
	v_and_b32_e32 v77, 0xffff0000, v73
	v_lshlrev_b32_e32 v106, 16, v74
	v_and_b32_e32 v107, 0xffff0000, v74
	v_lshlrev_b32_e32 v74, 16, v81
	v_and_b32_e32 v75, 0xffff0000, v81
	v_lshlrev_b32_e32 v72, 16, v80
	v_and_b32_e32 v73, 0xffff0000, v80
	v_pk_mul_f32 v[80:81], v[18:19], v[102:103]
	v_pk_fma_f32 v[68:69], v[40:41], v[74:75], v[68:69]
	v_pk_fma_f32 v[66:67], v[6:7], v[66:67], v[80:81]
	v_add_f32_e32 v119, 1.0, v119
	v_pk_fma_f32 v[66:67], v[34:35], v[76:77], v[66:67]
	v_mul_f32_e32 v64, v64, v118
	v_rcp_f32_e32 v119, v119
	v_mul_f32_e32 v64, v68, v64
	v_mul_f32_e32 v68, 0xbfb8aa3b, v66
	v_mul_f32_e32 v118, 0xbfb8aa3b, v67
	v_exp_f32_e32 v68, v68
	v_exp_f32_e32 v118, v118
	v_mul_f32_e32 v65, v65, v119
	v_mul_f32_e32 v65, v69, v65
	v_add_f32_e32 v68, 1.0, v68
	v_add_f32_e32 v69, 1.0, v118
	v_lshlrev_b32_e32 v70, 16, v71
	v_and_b32_e32 v71, 0xffff0000, v71
	v_pk_mul_f32 v[80:81], v[26:27], v[106:107]
	v_rcp_f32_e32 v68, v68
	v_rcp_f32_e32 v69, v69
	v_pk_fma_f32 v[70:71], v[10:11], v[70:71], v[80:81]
	v_lshlrev_b32_e32 v80, 16, v95
	v_and_b32_e32 v81, 0xffff0000, v95
	v_pk_mul_f32 v[120:121], v[20:21], v[108:109]
	v_lshlrev_b32_e32 v98, 16, v87
	v_and_b32_e32 v99, 0xffff0000, v87
	v_pk_fma_f32 v[80:81], v[0:1], v[80:81], v[120:121]
	v_cvt_pk_bf16_f32 v64, v64, v65
	v_mul_f32_e32 v65, v66, v68
	v_pk_fma_f32 v[80:81], v[36:37], v[98:99], v[80:81]
	v_mul_f32_e32 v66, v67, v69
	v_mul_f32_e32 v67, 0xbfb8aa3b, v80
	v_mul_f32_e32 v68, 0xbfb8aa3b, v81
	v_exp_f32_e32 v67, v67
	v_exp_f32_e32 v68, v68
	v_pk_fma_f32 v[70:71], v[42:43], v[72:73], v[70:71]
	v_lshlrev_b32_e32 v94, 16, v86
	v_add_f32_e32 v67, 1.0, v67
	v_add_f32_e32 v68, 1.0, v68
	v_rcp_f32_e32 v67, v67
	v_rcp_f32_e32 v68, v68
	v_and_b32_e32 v95, 0xffff0000, v86
	v_pk_fma_f32 v[82:83], v[38:39], v[94:95], v[82:83]
	v_mul_f32_e32 v65, v70, v65
	v_mul_f32_e32 v66, v71, v66
	v_cvt_pk_bf16_f32 v65, v65, v66
	v_mul_f32_e32 v66, v80, v67
	v_mul_f32_e32 v67, v81, v68
	v_mul_f32_e32 v68, 0xbfb8aa3b, v82
	v_mul_f32_e32 v69, 0xbfb8aa3b, v83
	v_exp_f32_e32 v68, v68
	v_exp_f32_e32 v69, v69
	v_lshlrev_b32_e32 v112, 16, v113
	v_and_b32_e32 v113, 0xffff0000, v113
	v_add_f32_e32 v68, 1.0, v68
	v_add_f32_e32 v69, 1.0, v69
	v_pk_mul_f32 v[120:121], v[28:29], v[112:113]
	v_rcp_f32_e32 v68, v68
	v_rcp_f32_e32 v69, v69
	v_lshlrev_b32_e32 v86, 16, v84
	v_and_b32_e32 v87, 0xffff0000, v84
	v_pk_fma_f32 v[92:93], v[12:13], v[92:93], v[120:121]
	s_cmp_gt_i32 s8, 15
	v_pk_fma_f32 v[92:93], v[44:45], v[86:87], v[92:93]
	v_lshlrev_b32_e32 v84, 16, v85
	v_and_b32_e32 v85, 0xffff0000, v85
	v_mul_f32_e32 v66, v92, v66
	v_mul_f32_e32 v67, v93, v67
	s_cselect_b32 s18, -16, 0x2000
	v_pk_fma_f32 v[96:97], v[46:47], v[84:85], v[96:97]
	v_cvt_pk_bf16_f32 v66, v66, v67
	v_mul_f32_e32 v67, v82, v68
	v_mul_f32_e32 v68, v83, v69
	s_cselect_b32 s13, -1, 0
	s_add_u32 s18, s8, s18
	v_mul_f32_e32 v67, v96, v67
	v_mul_f32_e32 v68, v97, v68
	s_addc_u32 s13, s9, s13
	v_cvt_pk_bf16_f32 v67, v67, v68
	s_mulk_i32 s13, 0x2c00
	v_mad_u64_u32 v[68:69], s[28:29], s18, v204, v[90:91]
	v_add_u32_e32 v69, s13, v69
	s_add_i32 s13, s8, 1
	global_store_dwordx4 v[68:69], v[64:67], off
	s_cmp_ge_i32 s13, s7
	v_lshlrev_b32_e32 v96, 16, v128
	v_and_b32_e32 v97, 0xffff0000, v128
	v_lshlrev_b32_e32 v92, 16, v127
	v_and_b32_e32 v93, 0xffff0000, v127
	v_lshlrev_b32_e32 v82, 16, v124
	v_and_b32_e32 v83, 0xffff0000, v124
	v_lshlrev_b32_e32 v80, 16, v123
	v_and_b32_e32 v81, 0xffff0000, v123
	v_lshlrev_b32_e32 v70, 16, v126
	v_and_b32_e32 v71, 0xffff0000, v126
	v_lshlrev_b32_e32 v68, 16, v125
	v_and_b32_e32 v69, 0xffff0000, v125
	v_lshlrev_b32_e32 v66, 16, v122
	v_and_b32_e32 v67, 0xffff0000, v122
	v_lshlrev_b32_e32 v64, 16, v117
	v_and_b32_e32 v65, 0xffff0000, v117
	s_cbranch_scc1 .LBB0_100
; __device__ __forceinline__ unsigned cvt_pk_bf16(float lo, float hi) { unsigned r; asm volatile("v_cvt_pk_bf16_f32 %0, %1, %2" : "=v"(r) : "v"(lo), "v"(hi)); return r; }
; __device__ __forceinline__ float bf_lo(unsigned w) { return __uint_as_float(w << 16); }
; __device__ __forceinline__ float bf_hi(unsigned w) { return __uint_as_float(w & 0xffff0000u); }
; __global__ void __launch_bounds__(512, 2) mk_fwd(Args a) {
;     ...
;                     for (int i = 0; i < 4; ++i) { const int lg = lb + i; if (lg < l1) {
;                         f32x4 av[2], bv[2];
; #pragma unroll
;                         for (int hh = 0; hh < 2; ++hh) {
;                             f32x4 x0, x1, x2, y0, y1, y2;
;                             const unsigned a0 = hh ? x[i][0].z : x[i][0].x, a1 = hh ? x[i][0].w : x[i][0].y, b0 = hh ? x[i + 1][0].z : x[i + 1][0].x, b1 = hh ? x[i + 1][0].w : x[i + 1][0].y, c0 = hh ? x[i + 2][0].z : x[i + 2][0].x, c1 = hh ? x[i + 2][0].w : x[i + 2][0].y;
;                             x0 = (f32x4){bf_lo(a0), bf_hi(a0), bf_lo(a1), bf_hi(a1)}; x1 = (f32x4){bf_lo(b0), bf_hi(b0), bf_lo(b1), bf_hi(b1)}; x2 = (f32x4){bf_lo(c0), bf_hi(c0), bf_lo(c1), bf_hi(c1)};
;                             const unsigned d0 = hh ? x[i][1].z : x[i][1].x, d1 = hh ? x[i][1].w : x[i][1].y, e0 = hh ? x[i + 1][1].z : x[i + 1][1].x, e1 = hh ? x[i + 1][1].w : x[i + 1][1].y, f0 = hh ? x[i + 2][1].z : x[i + 2][1].x, f1 = hh ? x[i + 2][1].w : x[i + 2][1].y;
;                             y0 = (f32x4){bf_lo(d0), bf_hi(d0), bf_lo(d1), bf_hi(d1)}; y1 = (f32x4){bf_lo(e0), bf_hi(e0), bf_lo(e1), bf_hi(e1)}; y2 = (f32x4){bf_lo(f0), bf_hi(f0), bf_lo(f1), bf_hi(f1)};
;                             av[hh] = wt[0][0][hh] * x0 + wt[1][0][hh] * x1 + wt[2][0][hh] * x2;
;                             bv[hh] = wt[0][1][hh] * y0 + wt[1][1][hh] * y1 + wt[2][1][hh] * y2; }
;                         u32x4 o;
;                         o.x = cvt_pk_bf16(av[0][0] * sigm(av[0][0]) * bv[0][0], av[0][1] * sigm(av[0][1]) * bv[0][1]); o.y = cvt_pk_bf16(av[0][2] * sigm(av[0][2]) * bv[0][2], av[0][3] * sigm(av[0][3]) * bv[0][3]);
;                         o.z = cvt_pk_bf16(av[1][0] * sigm(av[1][0]) * bv[1][0], av[1][1] * sigm(av[1][1]) * bv[1][1]); o.w = cvt_pk_bf16(av[1][2] * sigm(av[1][2]) * bv[1][2], av[1][3] * sigm(av[1][3]) * bv[1][3]);
;                         *(u32x4*)(GT + (size_t)phys_of(lg) * DFF + c) = o; } }
	v_pk_mul_f32 v[120:121], v[16:17], v[78:79]
	v_pk_mul_f32 v[118:119], v[18:19], v[76:77]
	v_pk_fma_f32 v[100:101], v[4:5], v[100:101], v[120:121]
	v_pk_fma_f32 v[102:103], v[6:7], v[102:103], v[118:119]
	v_pk_fma_f32 v[100:101], v[32:33], v[96:97], v[100:101]
	v_pk_mul_f32 v[118:119], v[26:27], v[72:73]
	v_mul_f32_e32 v117, 0xbfb8aa3b, v100
	v_exp_f32_e32 v117, v117
	v_pk_fma_f32 v[106:107], v[10:11], v[106:107], v[118:119]
	v_pk_mul_f32 v[118:119], v[22:23], v[94:95]
	v_pk_mul_f32 v[120:121], v[24:25], v[74:75]
	v_pk_fma_f32 v[110:111], v[2:3], v[110:111], v[118:119]
	v_pk_mul_f32 v[118:119], v[30:31], v[84:85]
	v_add_f32_e32 v117, 1.0, v117
	v_pk_fma_f32 v[114:115], v[14:15], v[114:115], v[118:119]
	v_mul_f32_e32 v118, 0xbfb8aa3b, v101
	v_exp_f32_e32 v118, v118
	v_rcp_f32_e32 v117, v117
	v_pk_fma_f32 v[104:105], v[8:9], v[104:105], v[120:121]
	v_pk_fma_f32 v[102:103], v[34:35], v[92:93], v[102:103]
	v_pk_fma_f32 v[104:105], v[40:41], v[82:83], v[104:105]
	v_add_f32_e32 v118, 1.0, v118
	v_mul_f32_e32 v100, v100, v117
	v_rcp_f32_e32 v118, v118
	v_mul_f32_e32 v100, v104, v100
	v_mul_f32_e32 v104, 0xbfb8aa3b, v102
	v_mul_f32_e32 v117, 0xbfb8aa3b, v103
	v_exp_f32_e32 v104, v104
	v_exp_f32_e32 v117, v117
	v_mul_f32_e32 v101, v101, v118
	v_mul_f32_e32 v101, v105, v101
	v_add_f32_e32 v104, 1.0, v104
	v_add_f32_e32 v105, 1.0, v117
	v_rcp_f32_e32 v104, v104
	v_rcp_f32_e32 v105, v105
	v_pk_mul_f32 v[120:121], v[20:21], v[98:99]
	v_cvt_pk_bf16_f32 v100, v100, v101
	v_mul_f32_e32 v101, v102, v104
	v_pk_fma_f32 v[108:109], v[0:1], v[108:109], v[120:121]
	v_mul_f32_e32 v102, v103, v105
	v_pk_fma_f32 v[108:109], v[36:37], v[70:71], v[108:109]
	v_pk_fma_f32 v[106:107], v[42:43], v[80:81], v[106:107]
	v_mul_f32_e32 v103, 0xbfb8aa3b, v108
	v_mul_f32_e32 v104, 0xbfb8aa3b, v109
	v_exp_f32_e32 v103, v103
	v_exp_f32_e32 v104, v104
	v_pk_fma_f32 v[110:111], v[38:39], v[68:69], v[110:111]
	v_mul_f32_e32 v101, v106, v101
	v_add_f32_e32 v103, 1.0, v103
	v_add_f32_e32 v104, 1.0, v104
	v_rcp_f32_e32 v103, v103
	v_rcp_f32_e32 v104, v104
	v_mul_f32_e32 v102, v107, v102
	v_cvt_pk_bf16_f32 v101, v101, v102
	v_mul_f32_e32 v102, v108, v103
	v_mul_f32_e32 v103, v109, v104
	v_mul_f32_e32 v104, 0xbfb8aa3b, v110
	v_mul_f32_e32 v105, 0xbfb8aa3b, v111
	v_exp_f32_e32 v104, v104
	v_exp_f32_e32 v105, v105
	v_pk_mul_f32 v[120:121], v[28:29], v[86:87]
	s_cmp_gt_i32 s8, 14
	v_add_f32_e32 v104, 1.0, v104
	v_add_f32_e32 v105, 1.0, v105
	v_rcp_f32_e32 v104, v104
	v_rcp_f32_e32 v105, v105
	v_pk_fma_f32 v[112:113], v[12:13], v[112:113], v[120:121]
	s_cselect_b32 s18, -16, 0x2000
	v_pk_fma_f32 v[112:113], v[44:45], v[66:67], v[112:113]
	s_cselect_b32 s13, -1, 0
	s_add_u32 s18, s8, s18
	v_mul_f32_e32 v102, v112, v102
	v_mul_f32_e32 v103, v113, v103
	s_addc_u32 s13, s9, s13
	v_pk_fma_f32 v[114:115], v[46:47], v[64:65], v[114:115]
	v_cvt_pk_bf16_f32 v102, v102, v103
	v_mul_f32_e32 v103, v110, v104
	v_mul_f32_e32 v104, v111, v105
	s_add_u32 s18, s18, 1
	v_mul_f32_e32 v103, v114, v103
	v_mul_f32_e32 v104, v115, v104
	s_addc_u32 s13, s13, 0
	v_cvt_pk_bf16_f32 v103, v103, v104
	s_mulk_i32 s13, 0x2c00
	v_mad_u64_u32 v[104:105], s[28:29], s18, v204, v[90:91]
	v_add_u32_e32 v105, s13, v105
	global_store_dwordx4 v[104:105], v[100:103], off

; __device__ __forceinline__ void attn_unit(const bf16_t* __restrict__ Qb, const bf16_t* __restrict__ Kh, const bf16_t* __restrict__ Vh, bf16_t* __restrict__ Ob,
;                                           LAS unsigned char* lds, float MB, int tid, int nrows, int t0, int t1, float* part, float* partl) {
;     const int wid = __builtin_amdgcn_readfirstlane(tid >> 6), lane = tid & 63, r32 = lane & 31, hi = lane >> 5;
;     LAS unsigned char* V_lds = lds + LDS_V; LAS unsigned char* K_lds = lds + LDS_K;
;     LAS float* li_l = (LAS float*)(lds + LDS_WS) + wid * 64;
;     const bool act = wid * 32 < nrows;
;     float l_reg = 0.f; f32x16 o[4] = {}; bf16x8 qr[QREG];
;     LAS unsigned char* qt = lds + LDS_QT + wid * ((12 - QREG) * 1024) + lane * 16;
;     const unsigned qo = (unsigned)((wid * 32 + r32) * LDQ + hi * 8) * 2u;
; #pragma unroll
;     for (int d0 = 0; d0 < QREG; ++d0) qr[d0] = *(const bf16x8*)((const char*)Qb + qo + d0 * 32);
; #pragma unroll
;     for (int d0 = QREG; d0 < 12; ++d0) *(LAS bf16x8*)(qt + (d0 - QREG) * 1024) = *(const bf16x8*)((const char*)Qb + qo + d0 * 32);
;     unsigned ko[3], vo[2];
; #pragma unroll
;     for (int i = 0; i < 3; ++i) { const int sl = tid + 512 * i, row = sl / 24, pc = sl - row * 24, ch = pc ^ ((row >> 1) & 7); ko[i] = (unsigned)(row * LDKK + ch * 8) * 2u; }
; #pragma unroll
;     for (int i = 0; i < 2; ++i) { const int sl = tid + 512 * i, sub = sl >> 5, kk = (sub >> 2) * 8 + ((sl >> 2) & 7), c = (sub & 3) * 32 + (sl & 3) * 8;
;         const int kx = (kk & ~0xC) | ((kk & 4) << 1) | ((kk & 8) >> 1); vo[i] = (unsigned)(kx * LDV + c) * 2u; }
;     const int vb0 = (int)(unsigned)(uintptr_t)V_lds + v_rd_base(lane);
;     const unsigned ldw = (unsigned)wid * 1024u;
;     ...
;     f32x16 p0, p1; bf16x8 pa0, pa1, pa2, pa3;
;     SDMA(t0 * KVBLK, 0); asm volatile("s_waitcnt vmcnt(0)" ::: "memory"); __syncthreads();
; __global__ void __launch_bounds__(512, 2) mk_fwd(Args a) {
;     ...
;                 for (int rep = 0; rep < ATT_REPEAT; ++rep) {
;                 float* PM = (float*)(ws + O_PM);
;                 const int nr = (512 - bx + G - 1) / G, mp0 = (G >= 136 + 16 * NMP) ? bx - 136 : bx, mstep = (G >= 136 + 16 * NMP) ? G : G;
;                 for (int it = 0;; ++it) { const bool mt = it >= nr; const int mp = mp0 + (it - nr) * mstep;
;                     if (mt && (mp < 0 || mp >= 16 * NMP)) break;
.LBB0_133:
	s_lshl_b32 s28, s28, 5
	s_and_b32 s28, s28, 0x1f00
	s_and_b64 s[46:47], s[8:9], exec
	s_cselect_b32 s48, 0x2000, s28
	s_mul_i32 s28, s29, -7
	s_cselect_b32 s49, 0, 0
	s_add_i32 s28, s28, s36
	s_mulk_i32 s28, 0x81
	s_and_b64 s[46:47], s[8:9], exec
	s_cselect_b32 s28, s28, 0
	s_mul_hi_i32 s33, s28, 0x92492493
	s_add_i32 s33, s33, s28
	s_lshr_b32 s37, s33, 31
	s_ashr_i32 s33, s33, 2
	s_add_i32 s33, s33, s37
	s_and_b64 s[46:47], s[8:9], exec
	s_cselect_b32 s46, s33, 0
	s_addk_i32 s28, 0x81
	s_mul_hi_i32 s33, s28, 0x92492493
	s_add_i32 s33, s33, s28
	s_lshr_b32 s28, s33, 31
	s_ashr_i32 s33, s33, 2
	s_add_i32 s33, s33, s28
	s_and_b64 s[50:51], s[8:9], exec
	s_mul_i32 s28, s48, 0x1800
	s_cselect_b32 s47, s33, 0x81
	s_add_u32 s28, s84, s28
	s_mul_i32 s50, s29, 0xc0
	s_addc_u32 s33, s85, 0
	s_ashr_i32 s51, s50, 31
	s_lshl_b64 s[50:51], s[50:51], 1
	s_add_u32 s52, s28, s50
	s_addc_u32 s53, s33, s51
	s_add_u32 s54, s13, s50
	s_addc_u32 s55, s18, s51
	s_lshl_b32 s50, s29, 8
	s_ashr_i32 s51, s50, 31
	s_lshl_b64 s[50:51], s[50:51], 1
	v_readlane_b32 s42, v254, 40
	v_readlane_b32 s43, v254, 41
	s_add_u32 s56, s42, s50
	v_readfirstlane_b32 s37, v152
	s_addc_u32 s57, s43, s51
	s_ashr_i32 s33, s37, 6
	s_lshl_b32 s28, s33, 5
	v_and_b32_e32 v0, 15, v150
	v_or_b32_e32 v0, s28, v0
	v_mul_lo_u32 v0, v0, s5
	v_and_b32_e32 v144, 0x30, v150
	v_or_b32_e32 v144, v0, v144
	s_cmp_lt_i32 s28, s26
	v_lshl_add_u64 v[0:1], s[52:53], 0, v[144:145]
	s_cselect_b64 s[50:51], -1, 0
	s_lshl_b32 s52, s46, 6
	s_ashr_i32 s53, s52, 31
	s_lshl_b32 s42, s33, 10
	s_lshl_b64 s[62:63], s[52:53], 13
	s_mul_i32 s43, s46, 0x60000
	v_add_co_u32_e32 v2, vcc, 0x18000, v0
	s_nop 1
	v_addc_co_u32_e32 v3, vcc, 0, v1, vcc
	global_load_dwordx4 v[96:99], v[0:1], off
	global_load_dwordx4 v[100:103], v[0:1], off offset:64
	global_load_dwordx4 v[104:107], v[0:1], off offset:128
	global_load_dwordx4 v[108:111], v[0:1], off offset:192
	global_load_dwordx4 v[112:115], v[0:1], off offset:256
	global_load_dwordx4 v[116:119], v[0:1], off offset:320
	global_load_dwordx4 v[120:123], v[2:3], off
	global_load_dwordx4 v[124:127], v[2:3], off offset:64
	global_load_dwordx4 v[128:131], v[2:3], off offset:128
	global_load_dwordx4 v[132:135], v[2:3], off offset:192
	global_load_dwordx4 v[136:139], v[2:3], off offset:256
	global_load_dwordx4 v[140:143], v[2:3], off offset:320
	s_mul_hi_i32 s53, s52, 0x1800
	s_add_u32 s60, s54, s43
	s_addc_u32 s61, s55, s53
	s_add_i32 s58, s42, 0
	s_add_i32 m0, s58, 0x8000
	v_lshl_add_u64 v[0:1], s[60:61], 0, v[156:157]
	s_add_i32 s59, s58, 0xa000
	global_load_lds_dwordx4 v[0:1], off
	v_lshl_add_u64 v[0:1], s[60:61], 0, v[158:159]
	s_mov_b32 m0, s59
	v_mov_b32_e32 v15, 0
	global_load_lds_dwordx4 v[0:1], off
	v_lshl_add_u64 v[0:1], s[60:61], 0, v[160:161]
	s_add_i32 s60, s58, 0xc000
	s_add_u32 s62, s56, s62
	s_mov_b32 m0, s60
	s_addc_u32 s63, s57, s63
	global_load_lds_dwordx4 v[0:1], off
	v_lshl_add_u64 v[0:1], s[62:63], 0, v[162:163]
	v_lshl_add_u64 v[0:1], v[0:1], 0, s[20:21]
	s_mov_b32 m0, s58
	v_mov_b32_e32 v14, v15
	global_load_lds_dwordx4 v[0:1], off
	v_lshl_add_u64 v[0:1], s[62:63], 0, v[164:165]
	v_lshl_add_u64 v[0:1], v[0:1], 0, s[20:21]
	s_add_i32 m0, s58, 0x2000
	s_cmp_ge_i32 s46, s47
	global_load_lds_dwordx4 v[0:1], off
	s_waitcnt vmcnt(0)
	v_mov_b32_e32 v13, v15
	v_mov_b32_e32 v12, v15
	v_mov_b32_e32 v11, v15
	v_mov_b32_e32 v10, v15
	v_mov_b32_e32 v9, v15
	v_mov_b32_e32 v8, v15
	v_mov_b32_e32 v7, v15
	v_mov_b32_e32 v6, v15
	v_mov_b32_e32 v5, v15
	v_mov_b32_e32 v4, v15
	v_mov_b32_e32 v3, v15
	v_mov_b32_e32 v2, v15
	v_mov_b32_e32 v1, v15
	v_mov_b32_e32 v0, v15
	v_mov_b32_e32 v31, v15
	v_mov_b32_e32 v30, v15
	v_mov_b32_e32 v29, v15
	v_mov_b32_e32 v28, v15
	v_mov_b32_e32 v27, v15
	v_mov_b32_e32 v26, v15
	v_mov_b32_e32 v25, v15
	v_mov_b32_e32 v24, v15
	v_mov_b32_e32 v23, v15
	v_mov_b32_e32 v22, v15
	v_mov_b32_e32 v21, v15
	v_mov_b32_e32 v20, v15
	v_mov_b32_e32 v19, v15
	v_mov_b32_e32 v18, v15
	v_mov_b32_e32 v17, v15
	v_mov_b32_e32 v16, v15
	v_mov_b32_e32 v47, v15
	v_mov_b32_e32 v46, v15
	v_mov_b32_e32 v45, v15
	v_mov_b32_e32 v44, v15
	v_mov_b32_e32 v43, v15
	v_mov_b32_e32 v42, v15
	v_mov_b32_e32 v41, v15
	v_mov_b32_e32 v40, v15
	v_mov_b32_e32 v39, v15
	v_mov_b32_e32 v38, v15
	v_mov_b32_e32 v37, v15
	v_mov_b32_e32 v36, v15
	v_mov_b32_e32 v35, v15
	v_mov_b32_e32 v34, v15
	v_mov_b32_e32 v33, v15
	v_mov_b32_e32 v32, v15
	v_mov_b32_e32 v63, v15
	v_mov_b32_e32 v62, v15
	v_mov_b32_e32 v61, v15
	v_mov_b32_e32 v60, v15
	v_mov_b32_e32 v59, v15
	v_mov_b32_e32 v58, v15
	v_mov_b32_e32 v57, v15
	v_mov_b32_e32 v56, v15
	v_mov_b32_e32 v55, v15
	v_mov_b32_e32 v54, v15
	v_mov_b32_e32 v53, v15
	v_mov_b32_e32 v52, v15
	v_mov_b32_e32 v51, v15
	v_mov_b32_e32 v50, v15
	v_mov_b32_e32 v49, v15
	v_mov_b32_e32 v48, v15
	v_mov_b32_e32 v155, v15
	v_mov_b32_e32 v149, 0
	s_waitcnt vmcnt(0) lgkmcnt(0)
	s_barrier
	s_cbranch_scc0 .LBB0_136
	s_and_b64 s[46:47], s[8:9], s[50:51]
	s_andn2_b64 vcc, exec, s[46:47]
	s_mov_b64 s[52:53], -1
	s_cbranch_vccnz .LBB0_143

; __device__ __forceinline__ unsigned addpair(unsigned x, unsigned y, float sg) { return cvt_pk_bf16(bf_lo(x) + sg * bf_lo(y), bf_hi(x) + sg * bf_hi(y)); }
; __global__ void __launch_bounds__(512, 2) mk_fwd(Args a) {
;     ...
;             for (int lf = gw; lf < MH; lf += NGW) {
;                 const bool v = lf <= HF, pr2 = lf > 0 && lf < HF;
;                 const bf16_t* p1 = PA + (size_t)(v ? phys_of(lf) : 0) * NPA; const bf16_t* p2 = PA + (size_t)(pr2 ? phys_of(LSEQ - lf) : 0) * NPA;
; #pragma unroll
;                 for (int j = 0; j < 2; ++j) { const int c = (lane + 64 * j) * 8; u32x4 e = {0u, 0u, 0u, 0u}, o = {0u, 0u, 0u, 0u};
;                     if (v) { const u32x4 x = *(const u32x4*)(p1 + c); e = x;
;                         if (pr2) { const u32x4 y = *(const u32x4*)(p2 + c);
;                             e.x = addpair(x.x, y.x, 1.f); e.y = addpair(x.y, y.y, 1.f); e.z = addpair(x.z, y.z, 1.f); e.w = addpair(x.w, y.w, 1.f);
;                             o.x = addpair(x.x, y.x, -1.f); o.y = addpair(x.y, y.y, -1.f); o.z = addpair(x.z, y.z, -1.f); o.w = addpair(x.w, y.w, -1.f); } }
;                     *(u32x4*)(EO + (size_t)lf * 1024 + c) = e; *(u32x4*)(EO + (size_t)MH * 1024 + (size_t)lf * 1024 + c) = o; }
.LBB0_250:
	v_mov_b32_e32 v7, 0
	s_andn2_b64 vcc, exec, s[40:41]
	v_mov_b32_e32 v6, 0
	v_mov_b32_e32 v5, 0
	v_mov_b32_e32 v4, 0
	s_waitcnt lgkmcnt(0)
	v_mov_b32_e32 v3, 0
	v_mov_b32_e32 v2, 0
	v_mov_b32_e32 v1, 0
	v_mov_b32_e32 v0, 0
	s_cbranch_vccnz .LBB0_243
	v_lshl_add_u64 v[0:1], s[36:37], 1, v[16:17]
	global_load_dwordx4 v[4:7], v[0:1], off
	s_lshl_b64 s[14:15], s[34:35], 1
	s_add_u32 s14, s84, s14
	s_addc_u32 s15, s85, s15
	s_andn2_b64 vcc, exec, s[38:39]
	s_mov_b64 s[34:35], -1
	s_cbranch_vccnz .LBB0_253
	s_mov_b64 s[34:35], 0

; __device__ __forceinline__ unsigned addpair(unsigned x, unsigned y, float sg) { return cvt_pk_bf16(bf_lo(x) + sg * bf_lo(y), bf_hi(x) + sg * bf_hi(y)); }
; __global__ void __launch_bounds__(512, 2) mk_fwd(Args a) {
;     ...
;                 for (int j = 0; j < 2; ++j) { const int c = (lane + 64 * j) * 8; u32x4 e = {0u, 0u, 0u, 0u}, o = {0u, 0u, 0u, 0u};
;                     if (v) { const u32x4 x = *(const u32x4*)(p1 + c); e = x;
;                         if (pr2) { const u32x4 y = *(const u32x4*)(p2 + c);
;                             e.x = addpair(x.x, y.x, 1.f); e.y = addpair(x.y, y.y, 1.f); e.z = addpair(x.z, y.z, 1.f); e.w = addpair(x.w, y.w, 1.f);
;                             o.x = addpair(x.x, y.x, -1.f); o.y = addpair(x.y, y.y, -1.f); o.z = addpair(x.z, y.z, -1.f); o.w = addpair(x.w, y.w, -1.f); } }
;                     *(u32x4*)(EO + (size_t)lf * 1024 + c) = e; *(u32x4*)(EO + (size_t)MH * 1024 + (size_t)lf * 1024 + c) = o; }
.LBB0_255:
	v_add_co_u32_e32 v24, vcc, 0x23dc1000, v20
	s_nop 1
	v_addc_co_u32_e32 v25, vcc, 0, v21, vcc
	s_waitcnt vmcnt(0) lgkmcnt(0)
	global_store_dwordx4 v[24:25], v[4:7], off
	s_nop 1
	v_add_co_u32_e32 v4, vcc, 0x24641000, v20
	s_nop 1
	v_addc_co_u32_e32 v5, vcc, 0, v21, vcc
	global_store_dwordx4 v[4:5], v[8:11], off
	global_load_dwordx4 v[4:7], v[0:1], off offset:1024
	s_and_b64 vcc, exec, s[8:9]
	s_cbranch_vccnz .LBB0_242
	v_mov_b32_e32 v2, 0
	v_mov_b32_e32 v1, 0
	v_mov_b32_e32 v0, 0
	s_branch .LBB0_243

; __global__ void __launch_bounds__(512, 2) mk_fwd(Args a) {
;     ...
;                     if (l == 0) {
;                         const float* src = r < LREAL ? a.in[I_X] + (size_t)r * DM : (r < LSEQ ? a.in[I_META] + (size_t)(r - LREAL) * DM : nullptr);
; #pragma unroll
;                         for (int j = 0; j < 8; ++j) { v[j] = src ? *(const f32x4*)(src + (lane + 64 * (j >> 1)) * 8 + (j & 1) * 4) : (f32x4){0.f, 0.f, 0.f, 0.f}; }
;                     } else {
; #pragma unroll
;                         for (int j = 0; j < 8; ++j) v[j] = *(const f32x4*)(hr + (lane + 64 * (j >> 1)) * 8 + (j & 1) * 4);
;                     }
.LBB0_932:
	v_readlane_b32 s0, v254, 32
	v_readlane_b32 s1, v254, 33
	s_andn2_b64 vcc, exec, s[0:1]
	s_mov_b64 s[0:1], -1
	s_cbranch_vccnz .LBB0_934
	v_lshl_add_u64 v[0:1], s[64:65], 0, v[76:77]
	v_add_co_u32_e32 v4, vcc, 0x9901000, v0
	s_mov_b64 s[0:1], 0
	s_nop 0
	v_addc_co_u32_e32 v5, vcc, 0, v1, vcc
	global_load_dwordx4 v[0:3], v[4:5], off
	global_load_dwordx4 v[38:41], v[4:5], off offset:16
	s_waitcnt vmcnt(0)
	global_load_dwordx4 v[50:53], v[4:5], off offset:2048
	global_load_dwordx4 v[42:45], v[4:5], off offset:2064
	v_lshl_add_u64 v[4:5], s[64:65], 0, v[74:75]
	v_add_co_u32_e32 v4, vcc, 0x9901000, v4
	s_nop 1
	v_addc_co_u32_e32 v5, vcc, 0, v5, vcc
	global_load_dwordx4 v[54:57], v[4:5], off
	global_load_dwordx4 v[46:49], v[4:5], off offset:16
	v_lshl_add_u64 v[4:5], s[64:65], 0, v[72:73]
	v_add_co_u32_e32 v4, vcc, 0x9901000, v4
	s_nop 1
	v_addc_co_u32_e32 v5, vcc, 0, v5, vcc
	global_load_dwordx4 v[34:37], v[4:5], off
	global_load_dwordx4 v[30:33], v[4:5], off offset:16
